# as v131 but the deferred P3->P4a panel counter read is issued after the sub-unit-1 epilogue drain and checked just before the next gates are fetched (its round trip overlaps the epilogue math); same s
# speedup vs baseline: 1.0003x; 1.0003x over previous
.LBB0_924:
	v_mov_b32_e32 v136, v194
	v_mov_b32_e32 v138, v193
	s_lshl_b32 s8, s47, 8
	s_and_b32 s8, s8, 0x1f00
	s_add_i32 s8, s8, s31
	v_add_u32_e32 v172, s8, v138
	s_lshl_b32 s8, s46, 7
	s_and_b32 s8, s8, 0x380
	s_ashr_i32 s15, s46, 3
	s_or_b32 s8, s8, s34
	s_waitcnt vmcnt(0)
	s_cmp_lg_u32 s43, 1
	s_cbranch_scc1 .Lmy_pw1_a
	s_cmp_lg_u32 s30, 0
	s_cbranch_scc1 .Lmy_pw1_a
	s_load_dwordx2 vcc, s[74:75], 0xf8
	s_waitcnt lgkmcnt(0)
	s_add_u32 vcc_lo, vcc_lo, s100
	s_addc_u32 vcc_hi, vcc_hi, 0
	global_load_dword v175, v137, vcc sc1
.Lmy_pw1_a:
	s_nop 0
	v_lshlrev_b32_e32 v138, 16, v1
	v_and_b32_e32 v139, 0xffff0000, v1
	s_cmp_lt_u32 s46, 8
	v_pk_mul_f32 v[178:179], v[94:95], v[138:139]
	v_pk_fma_f32 v[94:95], v[94:95], v[138:139], v[170:171]
	v_lshlrev_b32_e32 v138, 16, v0
	v_and_b32_e32 v139, 0xffff0000, v0
	v_lshlrev_b32_e32 v170, 16, v2
	v_and_b32_e32 v171, 0xffff0000, v2
	v_lshlrev_b32_e32 v180, 16, v3
	v_and_b32_e32 v181, 0xffff0000, v3
	v_lshl_add_u32 v174, v136, 3, s8
	s_cselect_b64 s[8:9], -1, 0
	s_cmp_eq_u32 s15, 3
	v_pk_mul_f32 v[182:183], v[92:93], v[138:139]
	v_pk_mul_f32 v[184:185], v[88:89], v[170:171]
	v_pk_mul_f32 v[186:187], v[90:91], v[180:181]
	v_pk_fma_f32 v[92:93], v[92:93], v[138:139], v[168:169]
	v_pk_fma_f32 v[88:89], v[88:89], v[170:171], v[166:167]
	v_pk_fma_f32 v[90:91], v[90:91], v[180:181], v[162:163]
	s_cselect_b64 s[22:23], -1, 0
	s_cmp_lg_u32 s15, 3
	v_cndmask_b32_e64 v171, v95, v179, s[8:9]
	v_cndmask_b32_e64 v170, v94, v178, s[8:9]
	v_cndmask_b32_e64 v169, v93, v183, s[8:9]
	v_cndmask_b32_e64 v168, v92, v182, s[8:9]
	v_cndmask_b32_e64 v163, v91, v187, s[8:9]
	v_cndmask_b32_e64 v162, v90, v186, s[8:9]
	v_cndmask_b32_e64 v167, v89, v185, s[8:9]
	v_cndmask_b32_e64 v166, v88, v184, s[8:9]
	v_lshlrev_b32_e32 v88, 1, v174
	s_cbranch_scc1 .LBB0_926
	v_cvt_pk_bf16_f32 v90, v168, v169
	v_cvt_pk_bf16_f32 v91, v170, v171
	v_cvt_pk_bf16_f32 v92, v166, v167
	v_cvt_pk_bf16_f32 v93, v162, v163
	v_lshl_add_u32 v89, v172, 11, v88
	buffer_store_dwordx4 v[90:93], v89, s[84:87], 0 offen sc1

.LBB0_942:
	s_cmp_lg_u32 s43, 1
	s_cbranch_scc1 .Lmy_pw1_done
	s_cmp_lg_u32 s30, 0
	s_cbranch_scc1 .Lmy_pw1_done
	s_waitcnt vmcnt(0)
.Lmy_pw1_chk:
	v_cmp_lt_u32_e32 vcc, 7, v175
	s_cbranch_vccnz .Lmy_pw1_ok
	s_sleep 1
	s_load_dwordx2 vcc, s[74:75], 0xf8
	s_waitcnt lgkmcnt(0)
	s_add_u32 vcc_lo, vcc_lo, s100
	s_addc_u32 vcc_hi, vcc_hi, 0
	global_load_dword v175, v137, vcc sc1
	s_waitcnt vmcnt(0)
	s_branch .Lmy_pw1_chk
.Lmy_pw1_ok:
	buffer_inv sc1
	s_waitcnt vmcnt(0)
.Lmy_pw1_done:
	s_lshl_b32 s8, s15, 10
	s_addk_i32 s8, 0x400
	s_ashr_i32 s9, s8, 31
	s_lshl_b64 s[8:9], s[8:9], 1
	s_add_u32 s8, s2, s8
	s_addc_u32 s9, s3, s9
	v_ashrrev_i32_e32 v175, 31, v174
	v_ashrrev_i32_e32 v173, 31, v172
	v_lshl_add_u64 v[0:1], v[174:175], 1, s[8:9]
	v_lshlrev_b64 v[2:3], 13, v[172:173]
	v_lshl_add_u64 v[24:25], v[0:1], 0, v[2:3]
	v_add_co_u32_e32 v4, vcc, s87, v24
	s_nop 1
	v_addc_co_u32_e32 v5, vcc, 0, v25, vcc
	v_add_co_u32_e32 v8, vcc, s94, v24
	global_load_dwordx4 v[0:3], v[24:25], off
	s_nop 0
	global_load_dwordx4 v[4:7], v[4:5], off
	v_addc_co_u32_e32 v9, vcc, 0, v25, vcc
	v_add_co_u32_e32 v12, vcc, s95, v24
	s_nop 1
	v_addc_co_u32_e32 v13, vcc, 0, v25, vcc
	v_add_co_u32_e32 v16, vcc, 0x100000, v24
	global_load_dwordx4 v[8:11], v[8:9], off
	s_nop 0
	global_load_dwordx4 v[12:15], v[12:13], off
	v_addc_co_u32_e32 v17, vcc, 0, v25, vcc
	v_add_co_u32_e32 v20, vcc, 0x120000, v24
	s_nop 1
	v_addc_co_u32_e32 v21, vcc, 0, v25, vcc
	v_add_co_u32_e32 v26, vcc, 0x140000, v24
	global_load_dwordx4 v[16:19], v[16:17], off
	s_nop 0
	global_load_dwordx4 v[20:23], v[20:21], off
	v_addc_co_u32_e32 v27, vcc, 0, v25, vcc
	v_add_co_u32_e32 v28, vcc, 0x160000, v24
	s_nop 1
	v_addc_co_u32_e32 v29, vcc, 0, v25, vcc
	global_load_dwordx4 v[24:27], v[26:27], off
	s_nop 0
	global_load_dwordx4 v[28:31], v[28:29], off
	s_cmp_eq_u32 s43, 3
	s_mov_b64 s[8:9], -1
	s_cbranch_scc1 .LBB0_919
